# neighbourhood-attention bias lookups: unconditional LDS reads issued four at a time plus select, instead of 16 exec-masked read-wait pairs per key tile
# baseline (speedup 1.0000x reference)
.LBB0_1351:
	v_cndmask_b32_e64 v4, 0, 1, s[18:19]
	s_andn2_b64 vcc, exec, s[18:19]
	s_xor_b64 s[18:19], s[22:23], -1
	s_xor_b64 s[24:25], s[20:21], -1
	v_cmp_ne_u32_e64 s[20:21], 1, v4
	v_cndmask_b32_e64 v4, 0, 1, s[18:19]
	s_xor_b64 s[26:27], s[26:27], -1
	s_xor_b64 s[62:63], s[62:63], -1
	v_cmp_ne_u32_e64 s[18:19], 1, v4
	s_cbranch_vccnz .LBB0_1393
	v_mov_b32_e32 v67, 0xf149f2ca
	s_and_b64 vcc, exec, s[18:19]
	v_mov_b32_e32 v66, 0xf149f2ca
	v_mov_b32_e32 v65, 0xf149f2ca
	v_mov_b32_e32 v64, 0xf149f2ca
	s_cbranch_vccnz .LBB0_1362
	v_mov_b32_e32 v65, 0xf149f2ca
	v_mov_b32_e32 v64, 0xf149f2ca
	v_mov_b32_e32 v67, 0xf149f2ca
	v_mov_b32_e32 v66, 0xf149f2ca
	v_add_u32_e32 v132, s72, v113
	ds_read_b32 v132, v132 offset:37732
	v_add_u32_e32 v133, s72, v112
	ds_read_b32 v133, v133 offset:37732
	v_add_u32_e32 v134, s72, v111
	ds_read_b32 v134, v134 offset:37732
	v_add_u32_e32 v135, s72, v110
	ds_read_b32 v135, v135 offset:37732
	s_waitcnt lgkmcnt(0)
	v_add_f32_e32 v132, v68, v132
	v_cndmask_b32_e64 v64, v64, v132, s[0:1]
	v_add_f32_e32 v133, v69, v133
	v_cndmask_b32_e64 v65, v65, v133, s[4:5]
	v_add_f32_e32 v134, v70, v134
	v_cndmask_b32_e64 v66, v66, v134, s[6:7]
	v_add_f32_e32 v135, v71, v135
	v_cndmask_b32_e64 v67, v67, v135, s[8:9]
.LBB0_1355:
.LBB0_1357:
.LBB0_1359:
.LBB0_1361:
.LBB0_1362:
	v_mov_b32_e32 v123, 0xf149f2ca
	s_andn2_b64 vcc, exec, s[24:25]
	v_mov_b32_e32 v124, 0xf149f2ca
	v_mov_b32_e32 v4, 0xf149f2ca
	v_mov_b32_e32 v122, 0xf149f2ca
	s_cbranch_vccnz .LBB0_1372
	v_mov_b32_e32 v4, 0xf149f2ca
	v_mov_b32_e32 v122, 0xf149f2ca
	v_mov_b32_e32 v123, 0xf149f2ca
	v_mov_b32_e32 v124, 0xf149f2ca
	v_add_u32_e32 v132, s72, v109
	ds_read_b32 v132, v132 offset:37732
	v_add_u32_e32 v133, s72, v108
	ds_read_b32 v133, v133 offset:37732
	v_add_u32_e32 v134, s72, v107
	ds_read_b32 v134, v134 offset:37732
	v_add_u32_e32 v135, s72, v106
	ds_read_b32 v135, v135 offset:37732
	s_waitcnt lgkmcnt(0)
	v_add_f32_e32 v132, v76, v132
	v_cndmask_b32_e64 v122, v122, v132, s[34:35]
	v_add_f32_e32 v133, v77, v133
	v_cndmask_b32_e64 v4, v4, v133, s[84:85]
	v_add_f32_e32 v134, v78, v134
	v_cndmask_b32_e64 v124, v124, v134, s[86:87]
	v_add_f32_e32 v135, v79, v135
	v_cndmask_b32_e64 v123, v123, v135, s[48:49]
.LBB0_1365:
.LBB0_1367:
.LBB0_1369:
.LBB0_1371:
.LBB0_1372:
	v_mov_b32_e32 v127, 0xf149f2ca
	s_andn2_b64 vcc, exec, s[26:27]
	v_mov_b32_e32 v128, 0xf149f2ca
	v_mov_b32_e32 v125, 0xf149f2ca
	v_mov_b32_e32 v126, 0xf149f2ca
	s_cbranch_vccnz .LBB0_1382
	v_mov_b32_e32 v125, 0xf149f2ca
	v_mov_b32_e32 v126, 0xf149f2ca
	v_mov_b32_e32 v127, 0xf149f2ca
	v_mov_b32_e32 v128, 0xf149f2ca
	v_add_u32_e32 v132, s72, v105
	ds_read_b32 v132, v132 offset:37732
	v_add_u32_e32 v133, s72, v104
	ds_read_b32 v133, v133 offset:37732
	v_add_u32_e32 v134, s72, v103
	ds_read_b32 v134, v134 offset:37732
	v_add_u32_e32 v135, s72, v102
	ds_read_b32 v135, v135 offset:37732
	s_waitcnt lgkmcnt(0)
	v_add_f32_e32 v132, v72, v132
	v_cndmask_b32_e64 v126, v126, v132, s[94:95]
	v_add_f32_e32 v133, v73, v133
	v_cndmask_b32_e64 v125, v125, v133, s[40:41]
	v_add_f32_e32 v134, v74, v134
	v_cndmask_b32_e64 v128, v128, v134, s[54:55]
	v_add_f32_e32 v135, v75, v135
	v_cndmask_b32_e64 v127, v127, v135, s[56:57]
.LBB0_1375:
.LBB0_1377:
.LBB0_1379:
.LBB0_1381:
.LBB0_1382:
	v_mov_b32_e32 v68, 0xf149f2ca
	s_andn2_b64 vcc, exec, s[62:63]
	v_mov_b32_e32 v69, 0xf149f2ca
	v_mov_b32_e32 v7, 0xf149f2ca
	v_mov_b32_e32 v6, 0xf149f2ca
	s_cbranch_vccnz .LBB0_1392
	v_mov_b32_e32 v7, 0xf149f2ca
	v_mov_b32_e32 v6, 0xf149f2ca
	v_mov_b32_e32 v68, 0xf149f2ca
	v_mov_b32_e32 v69, 0xf149f2ca
	v_add_u32_e32 v132, s72, v101
	ds_read_b32 v132, v132 offset:37732
	v_add_u32_e32 v133, s72, v100
	ds_read_b32 v133, v133 offset:37732
	v_add_u32_e32 v134, s72, v99
	ds_read_b32 v134, v134 offset:37732
	v_add_u32_e32 v135, s72, v98
	ds_read_b32 v135, v135 offset:37732
	s_waitcnt lgkmcnt(0)
	v_add_f32_e32 v132, v60, v132
	v_cndmask_b32_e64 v6, v6, v132, s[10:11]
	v_add_f32_e32 v133, v61, v133
	v_cndmask_b32_e64 v7, v7, v133, s[12:13]
	v_add_f32_e32 v134, v62, v134
	v_cndmask_b32_e64 v69, v69, v134, s[14:15]
	v_add_f32_e32 v135, v63, v135
	v_cndmask_b32_e64 v68, v68, v135, s[16:17]
.LBB0_1385:
.LBB0_1387:
.LBB0_1389:
.LBB0_1391:
.LBB0_1392:
	v_mov_b32_e32 v63, v68
	v_mov_b32_e32 v62, v69
	v_mov_b64_e32 v[70:71], v[66:67]
	v_mov_b32_e32 v61, v7
	v_mov_b32_e32 v60, v6
	v_mov_b64_e32 v[68:69], v[64:65]
	s_branch .LBB0_1394

.LBB0_1416:
	s_and_b64 vcc, exec, s[20:21]
	s_cbranch_vccnz .LBB0_1458
	v_mov_b32_e32 v67, 0xf149f2ca
	s_and_b64 vcc, exec, s[18:19]
	v_mov_b32_e32 v66, 0xf149f2ca
	v_mov_b32_e32 v65, 0xf149f2ca
	v_mov_b32_e32 v64, 0xf149f2ca
	s_cbranch_vccnz .LBB0_1427
	v_mov_b32_e32 v65, 0xf149f2ca
	v_mov_b32_e32 v64, 0xf149f2ca
	v_mov_b32_e32 v67, 0xf149f2ca
	v_mov_b32_e32 v66, 0xf149f2ca
	v_add_u32_e32 v132, s72, v113
	ds_read_b32 v132, v132 offset:37856
	v_add_u32_e32 v133, s72, v112
	ds_read_b32 v133, v133 offset:37856
	v_add_u32_e32 v134, s72, v111
	ds_read_b32 v134, v134 offset:37856
	v_add_u32_e32 v135, s72, v110
	ds_read_b32 v135, v135 offset:37856
	s_waitcnt lgkmcnt(0)
	v_add_f32_e32 v132, v72, v132
	v_cndmask_b32_e64 v64, v64, v132, s[0:1]
	v_add_f32_e32 v133, v73, v133
	v_cndmask_b32_e64 v65, v65, v133, s[4:5]
	v_add_f32_e32 v134, v74, v134
	v_cndmask_b32_e64 v66, v66, v134, s[6:7]
	v_add_f32_e32 v135, v75, v135
	v_cndmask_b32_e64 v67, v67, v135, s[8:9]
.LBB0_1420:
.LBB0_1422:
.LBB0_1424:
.LBB0_1426:
.LBB0_1427:
	v_mov_b32_e32 v124, 0xf149f2ca
	s_and_b64 vcc, exec, s[22:23]
	v_mov_b32_e32 v125, 0xf149f2ca
	v_mov_b32_e32 v122, 0xf149f2ca
	v_mov_b32_e32 v123, 0xf149f2ca
	s_cbranch_vccnz .LBB0_1437
	v_mov_b32_e32 v122, 0xf149f2ca
	v_mov_b32_e32 v123, 0xf149f2ca
	v_mov_b32_e32 v124, 0xf149f2ca
	v_mov_b32_e32 v125, 0xf149f2ca
	v_add_u32_e32 v132, s72, v109
	ds_read_b32 v132, v132 offset:37856
	v_add_u32_e32 v133, s72, v108
	ds_read_b32 v133, v133 offset:37856
	v_add_u32_e32 v134, s72, v107
	ds_read_b32 v134, v134 offset:37856
	v_add_u32_e32 v135, s72, v106
	ds_read_b32 v135, v135 offset:37856
	s_waitcnt lgkmcnt(0)
	v_add_f32_e32 v132, v76, v132
	v_cndmask_b32_e64 v123, v123, v132, s[34:35]
	v_add_f32_e32 v133, v77, v133
	v_cndmask_b32_e64 v122, v122, v133, s[84:85]
	v_add_f32_e32 v134, v78, v134
	v_cndmask_b32_e64 v125, v125, v134, s[86:87]
	v_add_f32_e32 v135, v79, v135
	v_cndmask_b32_e64 v124, v124, v135, s[48:49]
.LBB0_1430:
.LBB0_1432:
.LBB0_1434:
.LBB0_1436:
.LBB0_1437:
	v_mov_b32_e32 v128, 0xf149f2ca
	s_and_b64 vcc, exec, s[24:25]
	v_mov_b32_e32 v129, 0xf149f2ca
	v_mov_b32_e32 v126, 0xf149f2ca
	v_mov_b32_e32 v127, 0xf149f2ca
	s_cbranch_vccnz .LBB0_1447
	v_mov_b32_e32 v126, 0xf149f2ca
	v_mov_b32_e32 v127, 0xf149f2ca
	v_mov_b32_e32 v128, 0xf149f2ca
	v_mov_b32_e32 v129, 0xf149f2ca
	v_add_u32_e32 v132, s72, v105
	ds_read_b32 v132, v132 offset:37856
	v_add_u32_e32 v133, s72, v104
	ds_read_b32 v133, v133 offset:37856
	v_add_u32_e32 v134, s72, v103
	ds_read_b32 v134, v134 offset:37856
	v_add_u32_e32 v135, s72, v102
	ds_read_b32 v135, v135 offset:37856
	s_waitcnt lgkmcnt(0)
	v_add_f32_e32 v132, v68, v132
	v_cndmask_b32_e64 v127, v127, v132, s[94:95]
	v_add_f32_e32 v133, v69, v133
	v_cndmask_b32_e64 v126, v126, v133, s[40:41]
	v_add_f32_e32 v134, v70, v134
	v_cndmask_b32_e64 v129, v129, v134, s[54:55]
	v_add_f32_e32 v135, v71, v135
	v_cndmask_b32_e64 v128, v128, v135, s[56:57]
.LBB0_1440:
.LBB0_1442:
.LBB0_1444:
.LBB0_1446:
.LBB0_1447:
	v_mov_b32_e32 v70, 0xf149f2ca
	s_and_b64 vcc, exec, s[26:27]
	v_mov_b32_e32 v71, 0xf149f2ca
	v_mov_b32_e32 v69, 0xf149f2ca
	v_mov_b32_e32 v68, 0xf149f2ca
	s_cbranch_vccnz .LBB0_1457
	v_mov_b32_e32 v69, 0xf149f2ca
	v_mov_b32_e32 v68, 0xf149f2ca
	v_mov_b32_e32 v70, 0xf149f2ca
	v_mov_b32_e32 v71, 0xf149f2ca
	v_add_u32_e32 v132, s72, v101
	ds_read_b32 v132, v132 offset:37856
	v_add_u32_e32 v133, s72, v100
	ds_read_b32 v133, v133 offset:37856
	v_add_u32_e32 v134, s72, v99
	ds_read_b32 v134, v134 offset:37856
	v_add_u32_e32 v135, s72, v98
	ds_read_b32 v135, v135 offset:37856
	s_waitcnt lgkmcnt(0)
	v_add_f32_e32 v132, v60, v132
	v_cndmask_b32_e64 v68, v68, v132, s[10:11]
	v_add_f32_e32 v133, v61, v133
	v_cndmask_b32_e64 v69, v69, v133, s[12:13]
	v_add_f32_e32 v134, v62, v134
	v_cndmask_b32_e64 v71, v71, v134, s[14:15]
	v_add_f32_e32 v135, v63, v135
	v_cndmask_b32_e64 v70, v70, v135, s[16:17]
.LBB0_1450:
.LBB0_1452:
.LBB0_1454:
.LBB0_1456:
.LBB0_1457:
	v_mov_b64_e32 v[74:75], v[66:67]
	v_mov_b32_e32 v63, v70
	v_mov_b32_e32 v62, v71
	v_mov_b32_e32 v61, v69
	v_mov_b32_e32 v60, v68
	v_mov_b64_e32 v[72:73], v[64:65]
	s_branch .LBB0_1459

.LBB0_3343:
.LBB0_3345:
.LBB0_3347:
.LBB0_3349:
.LBB0_3350:
	v_mov_b32_e32 v123, 0xf149f2ca
	s_andn2_b64 vcc, exec, s[24:25]
	v_mov_b32_e32 v124, 0xf149f2ca
	v_mov_b32_e32 v4, 0xf149f2ca
	v_mov_b32_e32 v122, 0xf149f2ca
	s_cbranch_vccnz .LBB0_3360
	v_mov_b32_e32 v4, 0xf149f2ca
	v_mov_b32_e32 v122, 0xf149f2ca
	v_mov_b32_e32 v123, 0xf149f2ca
	v_mov_b32_e32 v124, 0xf149f2ca
	v_add_u32_e32 v132, s72, v109
	ds_read_b32 v132, v132 offset:37732
	v_add_u32_e32 v133, s72, v108
	ds_read_b32 v133, v133 offset:37732
	v_add_u32_e32 v134, s72, v107
	ds_read_b32 v134, v134 offset:37732
	v_add_u32_e32 v135, s72, v106
	ds_read_b32 v135, v135 offset:37732
	s_waitcnt lgkmcnt(0)
	v_add_f32_e32 v132, v76, v132
	v_cndmask_b32_e64 v122, v122, v132, s[34:35]
	v_add_f32_e32 v133, v77, v133
	v_cndmask_b32_e64 v4, v4, v133, s[84:85]
	v_add_f32_e32 v134, v78, v134
	v_cndmask_b32_e64 v124, v124, v134, s[86:87]
	v_add_f32_e32 v135, v79, v135
	v_cndmask_b32_e64 v123, v123, v135, s[40:41]
.LBB0_3353:
.LBB0_3355:
.LBB0_3357:
.LBB0_3359:
.LBB0_3360:
	v_mov_b32_e32 v127, 0xf149f2ca
	s_andn2_b64 vcc, exec, s[26:27]
	v_mov_b32_e32 v128, 0xf149f2ca
	v_mov_b32_e32 v125, 0xf149f2ca
	v_mov_b32_e32 v126, 0xf149f2ca
	s_cbranch_vccnz .LBB0_3370
	v_mov_b32_e32 v125, 0xf149f2ca
	v_mov_b32_e32 v126, 0xf149f2ca
	v_mov_b32_e32 v127, 0xf149f2ca
	v_mov_b32_e32 v128, 0xf149f2ca
	v_add_u32_e32 v132, s72, v105
	ds_read_b32 v132, v132 offset:37732
	v_add_u32_e32 v133, s72, v104
	ds_read_b32 v133, v133 offset:37732
	v_add_u32_e32 v134, s72, v103
	ds_read_b32 v134, v134 offset:37732
	v_add_u32_e32 v135, s72, v102
	ds_read_b32 v135, v135 offset:37732
	s_waitcnt lgkmcnt(0)
	v_add_f32_e32 v132, v72, v132
	v_cndmask_b32_e64 v126, v126, v132, s[92:93]
	v_add_f32_e32 v133, v73, v133
	v_cndmask_b32_e64 v125, v125, v133, s[44:45]
	v_add_f32_e32 v134, v74, v134
	v_cndmask_b32_e64 v128, v128, v134, s[90:91]
	v_add_f32_e32 v135, v75, v135
	v_cndmask_b32_e64 v127, v127, v135, s[36:37]

.LBB0_3408:
.LBB0_3410:
.LBB0_3412:
.LBB0_3414:
.LBB0_3415:
	v_mov_b32_e32 v124, 0xf149f2ca
	s_and_b64 vcc, exec, s[22:23]
	v_mov_b32_e32 v125, 0xf149f2ca
	v_mov_b32_e32 v122, 0xf149f2ca
	v_mov_b32_e32 v123, 0xf149f2ca
	s_cbranch_vccnz .LBB0_3425
	v_mov_b32_e32 v122, 0xf149f2ca
	v_mov_b32_e32 v123, 0xf149f2ca
	v_mov_b32_e32 v124, 0xf149f2ca
	v_mov_b32_e32 v125, 0xf149f2ca
	v_add_u32_e32 v132, s72, v109
	ds_read_b32 v132, v132 offset:37856
	v_add_u32_e32 v133, s72, v108
	ds_read_b32 v133, v133 offset:37856
	v_add_u32_e32 v134, s72, v107
	ds_read_b32 v134, v134 offset:37856
	v_add_u32_e32 v135, s72, v106
	ds_read_b32 v135, v135 offset:37856
	s_waitcnt lgkmcnt(0)
	v_add_f32_e32 v132, v76, v132
	v_cndmask_b32_e64 v123, v123, v132, s[34:35]
	v_add_f32_e32 v133, v77, v133
	v_cndmask_b32_e64 v122, v122, v133, s[84:85]
	v_add_f32_e32 v134, v78, v134
	v_cndmask_b32_e64 v125, v125, v134, s[86:87]
	v_add_f32_e32 v135, v79, v135
	v_cndmask_b32_e64 v124, v124, v135, s[40:41]
.LBB0_3418:
.LBB0_3420:
.LBB0_3422:
.LBB0_3424:
.LBB0_3425:
	v_mov_b32_e32 v128, 0xf149f2ca
	s_and_b64 vcc, exec, s[24:25]
	v_mov_b32_e32 v129, 0xf149f2ca
	v_mov_b32_e32 v126, 0xf149f2ca
	v_mov_b32_e32 v127, 0xf149f2ca
	s_cbranch_vccnz .LBB0_3435
	v_mov_b32_e32 v126, 0xf149f2ca
	v_mov_b32_e32 v127, 0xf149f2ca
	v_mov_b32_e32 v128, 0xf149f2ca
	v_mov_b32_e32 v129, 0xf149f2ca
	v_add_u32_e32 v132, s72, v105
	ds_read_b32 v132, v132 offset:37856
	v_add_u32_e32 v133, s72, v104
	ds_read_b32 v133, v133 offset:37856
	v_add_u32_e32 v134, s72, v103
	ds_read_b32 v134, v134 offset:37856
	v_add_u32_e32 v135, s72, v102
	ds_read_b32 v135, v135 offset:37856
	s_waitcnt lgkmcnt(0)
	v_add_f32_e32 v132, v68, v132
	v_cndmask_b32_e64 v127, v127, v132, s[92:93]
	v_add_f32_e32 v133, v69, v133
	v_cndmask_b32_e64 v126, v126, v133, s[44:45]
	v_add_f32_e32 v134, v70, v134
	v_cndmask_b32_e64 v129, v129, v134, s[90:91]
	v_add_f32_e32 v135, v71, v135
	v_cndmask_b32_e64 v128, v128, v135, s[36:37]
